# GEMM K-loops: one static s_setprio 1 for the wave half with the EARLY LDS-DMA window (waves 0-3), reset after the K-loop
# speedup vs baseline: 1.0165x; 1.0009x over previous
; DI void lds_barrier() { asm volatile("s_waitcnt lgkmcnt(0)\n\ts_barrier" ::: "memory"); }
; #define G_LOAD(RA, RB, KT) { size_t as_ = astep, bs_ = bstep; asm volatile("" : "+s"(as_), "+s"(bs_)); \
;       _Pragma("unroll") for (int i = 0; i < 4; ++i) { RA[i] = *(const u32x4*)(Ag + i * as_ + (KT) * 64); RB[i] = *(const u32x4*)(Bg + i * bs_ + (KT) * 64); } }
; DI void gemm_run(const GemmCfg c, char* smem, float* const g_h, u16* const g_hb, float* const g_out, const int final_out) {
;     ...
;     f32x16 acc[2][4];
; #pragma unroll
;     for (int a = 0; a < 2; ++a)
; #pragma unroll
;       for (int b = 0; b < 4; ++b)
; #pragma unroll
;         for (int i = 0; i < 16; ++i) acc[a][b][i] = 0.f;
;     float ss[4] = {0.f, 0.f, 0.f, 0.f};
;     u32x4 ra0[4], rb0[4];
;     ...
;     G_LOAD(ra0, rb0, 0);
;     __syncthreads();
;     G_STORE(ra0, rb0, 0);
;     G_LOAD(ra0, rb0, 1);
;     lds_barrier();
.Lgemm_pf_skip:
	s_mov_b32 s0, 0
	s_nop 0
	v_writelane_b32 v255, s0, 51
	s_add_u32 s4, s4, 0x80
	s_addc_u32 s5, s5, 0
	s_add_u32 s6, s6, 0x80
	s_addc_u32 s7, s7, 0
	s_add_u32 m0, s8, 0x9000
	s_nop 0
	global_load_lds_dwordx4 v130, s[4:5]
	s_add_u32 m0, s8, 0x1b000
	s_nop 0
	global_load_lds_dwordx4 v134, s[6:7]
	s_add_u32 m0, s8, 0x9400
	s_nop 0
	global_load_lds_dwordx4 v131, s[4:5]
	s_add_u32 m0, s8, 0x1b400
	s_nop 0
	global_load_lds_dwordx4 v135, s[6:7]
	s_add_u32 m0, s8, 0x9800
	s_nop 0
	global_load_lds_dwordx4 v132, s[4:5]
	s_add_u32 m0, s8, 0x1b800
	s_nop 0
	global_load_lds_dwordx4 v136, s[6:7]
	s_add_u32 m0, s8, 0x9c00
	s_nop 0
	global_load_lds_dwordx4 v133, s[4:5]
	s_add_u32 m0, s8, 0x1bc00
	s_nop 0
	global_load_lds_dwordx4 v137, s[6:7]
	s_add_u32 s4, s4, 0x80
	s_addc_u32 s5, s5, 0
	s_add_u32 s6, s6, 0x80
	s_addc_u32 s7, s7, 0
	v_mov_b32_e32 v0, 0
	v_mov_b32_e32 v1, 0
	v_mov_b32_e32 v2, 0
	v_mov_b32_e32 v3, 0
	v_mov_b32_e32 v4, 0
	v_mov_b32_e32 v5, 0
	v_mov_b32_e32 v6, 0
	v_mov_b32_e32 v7, 0
	v_mov_b32_e32 v8, 0
	v_mov_b32_e32 v9, 0
	v_mov_b32_e32 v10, 0
	v_mov_b32_e32 v11, 0
	v_mov_b32_e32 v12, 0
	v_mov_b32_e32 v13, 0
	v_mov_b32_e32 v14, 0
	v_mov_b32_e32 v15, 0
	v_mov_b32_e32 v16, 0
	v_mov_b32_e32 v17, 0
	v_mov_b32_e32 v18, 0
	v_mov_b32_e32 v19, 0
	v_mov_b32_e32 v20, 0
	v_mov_b32_e32 v21, 0
	v_mov_b32_e32 v22, 0
	v_mov_b32_e32 v23, 0
	v_mov_b32_e32 v24, 0
	v_mov_b32_e32 v25, 0
	v_mov_b32_e32 v26, 0
	v_mov_b32_e32 v27, 0
	v_mov_b32_e32 v28, 0
	v_mov_b32_e32 v29, 0
	v_mov_b32_e32 v30, 0
	v_mov_b32_e32 v31, 0
	v_mov_b32_e32 v32, 0
	v_mov_b32_e32 v33, 0
	v_mov_b32_e32 v34, 0
	v_mov_b32_e32 v35, 0
	v_mov_b32_e32 v36, 0
	v_mov_b32_e32 v37, 0
	v_mov_b32_e32 v38, 0
	v_mov_b32_e32 v39, 0
	v_mov_b32_e32 v40, 0
	v_mov_b32_e32 v41, 0
	v_mov_b32_e32 v42, 0
	v_mov_b32_e32 v43, 0
	v_mov_b32_e32 v44, 0
	v_mov_b32_e32 v45, 0
	v_mov_b32_e32 v46, 0
	v_mov_b32_e32 v47, 0
	v_mov_b32_e32 v48, 0
	v_mov_b32_e32 v49, 0
	v_mov_b32_e32 v50, 0
	v_mov_b32_e32 v51, 0
	v_mov_b32_e32 v52, 0
	v_mov_b32_e32 v53, 0
	v_mov_b32_e32 v54, 0
	v_mov_b32_e32 v55, 0
	v_mov_b32_e32 v56, 0
	v_mov_b32_e32 v57, 0
	v_mov_b32_e32 v58, 0
	v_mov_b32_e32 v59, 0
	v_mov_b32_e32 v60, 0
	v_mov_b32_e32 v61, 0
	v_mov_b32_e32 v62, 0
	v_mov_b32_e32 v63, 0
	v_mov_b32_e32 v64, 0
	v_mov_b32_e32 v65, 0
	v_mov_b32_e32 v66, 0
	v_mov_b32_e32 v67, 0
	v_mov_b32_e32 v68, 0
	v_mov_b32_e32 v69, 0
	v_mov_b32_e32 v70, 0
	v_mov_b32_e32 v71, 0
	v_mov_b32_e32 v72, 0
	v_mov_b32_e32 v73, 0
	v_mov_b32_e32 v74, 0
	v_mov_b32_e32 v75, 0
	v_mov_b32_e32 v76, 0
	v_mov_b32_e32 v77, 0
	v_mov_b32_e32 v78, 0
	v_mov_b32_e32 v79, 0
	v_mov_b32_e32 v80, 0
	v_mov_b32_e32 v81, 0
	v_mov_b32_e32 v82, 0
	v_mov_b32_e32 v83, 0
	v_mov_b32_e32 v84, 0
	v_mov_b32_e32 v85, 0
	v_mov_b32_e32 v86, 0
	v_mov_b32_e32 v87, 0
	v_mov_b32_e32 v88, 0
	v_mov_b32_e32 v89, 0
	v_mov_b32_e32 v90, 0
	v_mov_b32_e32 v91, 0
	v_mov_b32_e32 v92, 0
	v_mov_b32_e32 v93, 0
	v_mov_b32_e32 v94, 0
	v_mov_b32_e32 v95, 0
	v_mov_b32_e32 v96, 0
	v_mov_b32_e32 v97, 0
	v_mov_b32_e32 v98, 0
	v_mov_b32_e32 v99, 0
	v_mov_b32_e32 v100, 0
	v_mov_b32_e32 v101, 0
	v_mov_b32_e32 v102, 0
	v_mov_b32_e32 v103, 0
	v_mov_b32_e32 v104, 0
	v_mov_b32_e32 v105, 0
	v_mov_b32_e32 v106, 0
	v_mov_b32_e32 v107, 0
	v_mov_b32_e32 v108, 0
	v_mov_b32_e32 v109, 0
	v_mov_b32_e32 v110, 0
	v_mov_b32_e32 v111, 0
	v_mov_b32_e32 v112, 0
	v_mov_b32_e32 v113, 0
	v_mov_b32_e32 v114, 0
	v_mov_b32_e32 v115, 0
	v_mov_b32_e32 v116, 0
	v_mov_b32_e32 v117, 0
	v_mov_b32_e32 v118, 0
	v_mov_b32_e32 v119, 0
	v_mov_b32_e32 v120, 0
	v_mov_b32_e32 v121, 0
	v_mov_b32_e32 v122, 0
	v_mov_b32_e32 v123, 0
	v_mov_b32_e32 v124, 0
	v_mov_b32_e32 v125, 0
	v_mov_b32_e32 v126, 0
	v_mov_b32_e32 v127, 0
	v_mov_b32_e32 v199, 0
	v_mov_b32_e32 v198, 0
	v_mov_b32_e32 v171, 0
	v_mov_b32_e32 v164, 0
	v_mov_b32_e32 v140, 0
	v_mov_b32_e32 v141, 0
	v_mov_b32_e32 v142, 0
	v_mov_b32_e32 v143, 0
	v_mov_b32_e32 v144, 0
	v_mov_b32_e32 v145, 0
	v_mov_b32_e32 v146, 0
	v_mov_b32_e32 v147, 0
	v_mov_b32_e32 v148, 0
	v_mov_b32_e32 v149, 0
	v_mov_b32_e32 v150, 0
	v_mov_b32_e32 v151, 0
	v_mov_b32_e32 v152, 0
	v_mov_b32_e32 v153, 0
	v_mov_b32_e32 v154, 0
	v_mov_b32_e32 v155, 0
	s_waitcnt vmcnt(8)
	s_mov_b32 s1, 0
	s_add_i32 s0, s68, 3
	s_barrier
	ds_read_b128 v[160:163], v194
	ds_read_b128 v[176:179], v194 offset:2048
	ds_read_b128 v[180:183], v194 offset:4096
	ds_read_b128 v[204:207], v195
	ds_read_b128 v[222:225], v195 offset:2048
	ds_read_b128 v[226:229], v195 offset:4096
	ds_read_b128 v[230:233], v195 offset:6144
	ds_read_b128 v[234:237], v195 offset:8192
	ds_read_b128 v[238:241], v195 offset:10240
	ds_read_b128 v[242:245], v195 offset:12288
	ds_read_b128 v[246:249], v195 offset:14336
	ds_read_b128 v[200:203], v194 offset:6144
	s_cmp_ge_u32 s8, 0x4000
	s_cbranch_scc1 .Lgemm_disp_late
	s_setprio 1
	s_cmp_eq_u32 s9, 0
	s_cbranch_scc1 .Lgemm_kloop_n
	s_cmp_eq_u32 s9, 2
	s_cbranch_scc1 .Lgemm_kloop_r1e
	s_branch .LBB0_112
